# up epilogue gate: the +1.0 adds as two v_pk_add_f32 with a (1.0,1.0) register pair
# speedup vs baseline: 1.0016x; 1.0016x over previous
.Lpeel_x_0:
	s_add_i32 s1, s50, 0xffffffbd
	s_cmpk_gt_i32 s50, 0x42
	s_cselect_b32 s1, s1, s50
	s_mul_i32 s23, s1, 0xf8
	s_cselect_b32 s2, 0x4000, 0
	s_cselect_b32 s3, 0x100, s37
	s_add_i32 s23, s23, s84
	v_add_u32_e32 v188, s88, v178
	s_mov_b32 s50, 0xbfb8aa3b
	s_mov_b32 s51, 0xbfb8aa3b
	v_mov_b32_e32 v236, 1.0
	v_mov_b32_e32 v237, 1.0
	ds_read_b128 v[126:129], v188
	ds_read_b128 v[122:125], v188 offset:128
	ds_read_b128 v[114:117], v188 offset:256
	ds_read_b128 v[118:121], v188 offset:384
	ds_read_b128 v[110:113], v188 offset:512
	ds_read_b128 v[106:109], v188 offset:640
	ds_read_b128 v[98:101], v188 offset:768
	ds_read_b128 v[102:105], v188 offset:896
	v_readlane_b32 s12, v252, 28
	v_readlane_b32 s13, v252, 29
	v_bfe_u32 v231, v202, 5, 1
	v_and_b32_e32 v174, 48, v180
	v_lshl_or_b32 v174, v231, 3, v174
	v_lshl_or_b32 v174, s0, 7, v174
	v_bfe_u32 v230, v202, 4, 1
	v_lshl_add_u32 v186, v177, 2, s23
	v_cmp_eq_u32_e32 vcc, 1, v230
	s_or_b64 s[52:53], s[42:43], vcc
	v_cmp_eq_u32_e32 vcc, 0, v230
	s_or_b64 s[54:55], s[44:45], vcc
	v_add_u32_e32 v186, v186, v230
	v_add_u32_e32 v187, s2, v186
	v_mul_u32_u24_e32 v187, 0x1600, v187
	v_lshl_add_u32 v187, v174, 1, v187
	s_waitcnt lgkmcnt(0)
	v_pk_fma_f32 v[190:191], v[158:159], v[122:123], v[118:119]
	v_pk_fma_f32 v[192:193], v[160:161], v[124:125], v[120:121]
	v_pk_fma_f32 v[194:195], v[154:155], v[106:107], v[102:103]
	v_pk_fma_f32 v[196:197], v[156:157], v[108:109], v[104:105]
	v_add_u32_e32 v230, 0, v186
	v_fmac_f32_dpp v190, v134, v126 row_ror:1 row_mask:0xf bank_mask:0xf
	v_fmac_f32_dpp v191, v135, v127 row_ror:1 row_mask:0xf bank_mask:0xf
	v_fmac_f32_dpp v192, v136, v128 row_ror:1 row_mask:0xf bank_mask:0xf
	v_fmac_f32_dpp v193, v137, v129 row_ror:1 row_mask:0xf bank_mask:0xf
	v_fmac_f32_dpp v194, v130, v110 row_ror:1 row_mask:0xf bank_mask:0xf
	v_fmac_f32_dpp v195, v131, v111 row_ror:1 row_mask:0xf bank_mask:0xf
	v_fmac_f32_dpp v196, v132, v112 row_ror:1 row_mask:0xf bank_mask:0xf
	v_fmac_f32_dpp v197, v133, v113 row_ror:1 row_mask:0xf bank_mask:0xf
	v_pk_fma_f32 v[190:191], v[150:151], v[114:115], v[190:191]
	v_pk_fma_f32 v[192:193], v[152:153], v[116:117], v[192:193]
	v_pk_fma_f32 v[194:195], v[146:147], v[98:99], v[194:195]
	v_pk_fma_f32 v[196:197], v[148:149], v[100:101], v[196:197]
	v_pk_mul_f32 v[198:199], v[190:191], s[50:51]
	v_pk_mul_f32 v[200:201], v[192:193], s[50:51]
	v_exp_f32_e32 v198, v198
	v_exp_f32_e32 v199, v199
	v_exp_f32_e32 v200, v200
	v_exp_f32_e32 v201, v201
	v_pk_add_f32 v[198:199], v[198:199], v[236:237]
	v_pk_add_f32 v[200:201], v[200:201], v[236:237]
	v_rcp_f32_e32 v198, v198
	v_rcp_f32_e32 v199, v199
	v_rcp_f32_e32 v200, v200
	v_rcp_f32_e32 v201, v201
	v_pk_mul_f32 v[190:191], v[190:191], v[198:199]
	v_pk_mul_f32 v[192:193], v[192:193], v[200:201]
	v_pk_mul_f32 v[190:191], v[190:191], v[194:195]
	v_pk_mul_f32 v[192:193], v[192:193], v[196:197]
	v_cvt_pk_bf16_f32 v232, v190, v191
	v_cvt_pk_bf16_f32 v233, v192, v193
	v_pk_fma_f32 v[190:191], v[150:151], v[122:123], v[118:119]
	v_pk_fma_f32 v[192:193], v[152:153], v[124:125], v[120:121]
	v_pk_fma_f32 v[194:195], v[146:147], v[106:107], v[102:103]
	v_pk_fma_f32 v[196:197], v[148:149], v[108:109], v[104:105]
	v_pk_fma_f32 v[190:191], v[158:159], v[126:127], v[190:191]
	v_pk_fma_f32 v[192:193], v[160:161], v[128:129], v[192:193]
	v_pk_fma_f32 v[194:195], v[154:155], v[110:111], v[194:195]
	v_pk_fma_f32 v[196:197], v[156:157], v[112:113], v[196:197]
	v_pk_fma_f32 v[190:191], v[142:143], v[114:115], v[190:191]
	v_pk_fma_f32 v[192:193], v[144:145], v[116:117], v[192:193]
	v_pk_fma_f32 v[194:195], v[138:139], v[98:99], v[194:195]
	v_pk_fma_f32 v[196:197], v[140:141], v[100:101], v[196:197]
	v_pk_mul_f32 v[198:199], v[190:191], s[50:51]
	v_pk_mul_f32 v[200:201], v[192:193], s[50:51]
	v_exp_f32_e32 v198, v198
	v_exp_f32_e32 v199, v199
	v_exp_f32_e32 v200, v200
	v_exp_f32_e32 v201, v201
	v_pk_add_f32 v[198:199], v[198:199], v[236:237]
	v_pk_add_f32 v[200:201], v[200:201], v[236:237]
	v_rcp_f32_e32 v198, v198
	v_rcp_f32_e32 v199, v199
	v_rcp_f32_e32 v200, v200
	v_rcp_f32_e32 v201, v201
	v_pk_mul_f32 v[190:191], v[190:191], v[198:199]
	v_pk_mul_f32 v[192:193], v[192:193], v[200:201]
	v_pk_mul_f32 v[190:191], v[190:191], v[194:195]
	v_pk_mul_f32 v[192:193], v[192:193], v[196:197]
	v_cvt_pk_bf16_f32 v234, v190, v191
	v_cvt_pk_bf16_f32 v235, v192, v193
	v_cmp_gt_i32_e32 vcc, s3, v230
	s_and_b64 vcc, vcc, s[52:53]
	s_nop 0
	v_permlane16_swap_b32_e32 v232, v234
	v_permlane16_swap_b32_e32 v233, v235
	s_and_saveexec_b64 s[0:1], vcc
	global_store_dwordx4 v187, v[232:235], s[12:13]
	s_mov_b64 exec, s[0:1]
	v_pk_fma_f32 v[190:191], v[142:143], v[122:123], v[118:119]
	v_pk_fma_f32 v[192:193], v[144:145], v[124:125], v[120:121]
	v_pk_fma_f32 v[194:195], v[138:139], v[106:107], v[102:103]
	v_pk_fma_f32 v[196:197], v[140:141], v[108:109], v[104:105]
	v_add_u32_e32 v230, 2, v186
	v_add_u32_e32 v231, 0x2c00, v187
	v_pk_fma_f32 v[190:191], v[150:151], v[126:127], v[190:191]
	v_pk_fma_f32 v[192:193], v[152:153], v[128:129], v[192:193]
	v_pk_fma_f32 v[194:195], v[146:147], v[110:111], v[194:195]
	v_pk_fma_f32 v[196:197], v[148:149], v[112:113], v[196:197]
	v_pk_fma_f32 v[190:191], v[134:135], v[114:115], v[190:191]
	v_pk_fma_f32 v[192:193], v[136:137], v[116:117], v[192:193]
	v_pk_fma_f32 v[194:195], v[130:131], v[98:99], v[194:195]
	v_pk_fma_f32 v[196:197], v[132:133], v[100:101], v[196:197]
	v_pk_mul_f32 v[198:199], v[190:191], s[50:51]
	v_pk_mul_f32 v[200:201], v[192:193], s[50:51]
	v_exp_f32_e32 v198, v198
	v_exp_f32_e32 v199, v199
	v_exp_f32_e32 v200, v200
	v_exp_f32_e32 v201, v201
	v_pk_add_f32 v[198:199], v[198:199], v[236:237]
	v_pk_add_f32 v[200:201], v[200:201], v[236:237]
	v_rcp_f32_e32 v198, v198
	v_rcp_f32_e32 v199, v199
	v_rcp_f32_e32 v200, v200
	v_rcp_f32_e32 v201, v201
	v_pk_mul_f32 v[190:191], v[190:191], v[198:199]
	v_pk_mul_f32 v[192:193], v[192:193], v[200:201]
	v_pk_mul_f32 v[190:191], v[190:191], v[194:195]
	v_pk_mul_f32 v[192:193], v[192:193], v[196:197]
	v_cvt_pk_bf16_f32 v232, v190, v191
	v_cvt_pk_bf16_f32 v233, v192, v193
	v_pk_fma_f32 v[190:191], v[134:135], v[122:123], v[118:119]
	v_pk_fma_f32 v[192:193], v[136:137], v[124:125], v[120:121]
	v_pk_fma_f32 v[194:195], v[130:131], v[106:107], v[102:103]
	v_pk_fma_f32 v[196:197], v[132:133], v[108:109], v[104:105]
	v_pk_fma_f32 v[190:191], v[142:143], v[126:127], v[190:191]
	v_pk_fma_f32 v[192:193], v[144:145], v[128:129], v[192:193]
	v_pk_fma_f32 v[194:195], v[138:139], v[110:111], v[194:195]
	v_pk_fma_f32 v[196:197], v[140:141], v[112:113], v[196:197]
	v_fmac_f32_dpp v190, v158, v114 row_ror:15 row_mask:0xf bank_mask:0xf
	v_fmac_f32_dpp v191, v159, v115 row_ror:15 row_mask:0xf bank_mask:0xf
	v_fmac_f32_dpp v192, v160, v116 row_ror:15 row_mask:0xf bank_mask:0xf
	v_fmac_f32_dpp v193, v161, v117 row_ror:15 row_mask:0xf bank_mask:0xf
	v_fmac_f32_dpp v194, v154, v98 row_ror:15 row_mask:0xf bank_mask:0xf
	v_fmac_f32_dpp v195, v155, v99 row_ror:15 row_mask:0xf bank_mask:0xf
	v_fmac_f32_dpp v196, v156, v100 row_ror:15 row_mask:0xf bank_mask:0xf
	v_fmac_f32_dpp v197, v157, v101 row_ror:15 row_mask:0xf bank_mask:0xf
	v_pk_mul_f32 v[198:199], v[190:191], s[50:51]
	v_pk_mul_f32 v[200:201], v[192:193], s[50:51]
	v_exp_f32_e32 v198, v198
	v_exp_f32_e32 v199, v199
	v_exp_f32_e32 v200, v200
	v_exp_f32_e32 v201, v201
	v_pk_add_f32 v[198:199], v[198:199], v[236:237]
	v_pk_add_f32 v[200:201], v[200:201], v[236:237]
	v_rcp_f32_e32 v198, v198
	v_rcp_f32_e32 v199, v199
	v_rcp_f32_e32 v200, v200
	v_rcp_f32_e32 v201, v201
	v_pk_mul_f32 v[190:191], v[190:191], v[198:199]
	v_pk_mul_f32 v[192:193], v[192:193], v[200:201]
	v_pk_mul_f32 v[190:191], v[190:191], v[194:195]
	v_pk_mul_f32 v[192:193], v[192:193], v[196:197]
	v_cvt_pk_bf16_f32 v234, v190, v191
	v_cvt_pk_bf16_f32 v235, v192, v193
	v_cmp_gt_i32_e32 vcc, s3, v230
	s_and_b64 vcc, vcc, s[54:55]
	s_nop 0
	v_permlane16_swap_b32_e32 v232, v234
	v_permlane16_swap_b32_e32 v233, v235
	s_and_saveexec_b64 s[0:1], vcc
	global_store_dwordx4 v231, v[232:235], s[12:13]
	s_mov_b64 exec, s[0:1]
	ds_read_b128 v[130:133], v188 offset:64
	ds_read_b128 v[134:137], v188 offset:192
	ds_read_b128 v[138:141], v188 offset:320
	ds_read_b128 v[142:145], v188 offset:448
	ds_read_b128 v[146:149], v188 offset:576
	ds_read_b128 v[150:153], v188 offset:704
	ds_read_b128 v[154:157], v188 offset:832
	ds_read_b128 v[158:161], v188 offset:960
	v_pk_fma_f32 v[190:191], v[94:95], v[122:123], v[118:119]
	v_pk_fma_f32 v[192:193], v[96:97], v[124:125], v[120:121]
	v_pk_fma_f32 v[194:195], v[90:91], v[106:107], v[102:103]
	v_pk_fma_f32 v[196:197], v[92:93], v[108:109], v[104:105]
	v_add_u32_e32 v230, 0x7c, v186
	v_add_u32_e32 v231, 0xaa800, v187
	v_fmac_f32_dpp v190, v70, v126 row_ror:1 row_mask:0xf bank_mask:0xf
	v_fmac_f32_dpp v191, v71, v127 row_ror:1 row_mask:0xf bank_mask:0xf
	v_fmac_f32_dpp v192, v72, v128 row_ror:1 row_mask:0xf bank_mask:0xf
	v_fmac_f32_dpp v193, v73, v129 row_ror:1 row_mask:0xf bank_mask:0xf
	v_fmac_f32_dpp v194, v66, v110 row_ror:1 row_mask:0xf bank_mask:0xf
	v_fmac_f32_dpp v195, v67, v111 row_ror:1 row_mask:0xf bank_mask:0xf
	v_fmac_f32_dpp v196, v68, v112 row_ror:1 row_mask:0xf bank_mask:0xf
	v_fmac_f32_dpp v197, v69, v113 row_ror:1 row_mask:0xf bank_mask:0xf
	v_pk_fma_f32 v[190:191], v[86:87], v[114:115], v[190:191]
	v_pk_fma_f32 v[192:193], v[88:89], v[116:117], v[192:193]
	v_pk_fma_f32 v[194:195], v[82:83], v[98:99], v[194:195]
	v_pk_fma_f32 v[196:197], v[84:85], v[100:101], v[196:197]
	v_pk_mul_f32 v[198:199], v[190:191], s[50:51]
	v_pk_mul_f32 v[200:201], v[192:193], s[50:51]
	v_exp_f32_e32 v198, v198
	v_exp_f32_e32 v199, v199
	v_exp_f32_e32 v200, v200
	v_exp_f32_e32 v201, v201
	v_pk_add_f32 v[198:199], v[198:199], v[236:237]
	v_pk_add_f32 v[200:201], v[200:201], v[236:237]
	v_rcp_f32_e32 v198, v198
	v_rcp_f32_e32 v199, v199
	v_rcp_f32_e32 v200, v200
	v_rcp_f32_e32 v201, v201
	v_pk_mul_f32 v[190:191], v[190:191], v[198:199]
	v_pk_mul_f32 v[192:193], v[192:193], v[200:201]
	v_pk_mul_f32 v[190:191], v[190:191], v[194:195]
	v_pk_mul_f32 v[192:193], v[192:193], v[196:197]
	v_cvt_pk_bf16_f32 v232, v190, v191
	v_cvt_pk_bf16_f32 v233, v192, v193
	v_pk_fma_f32 v[190:191], v[86:87], v[122:123], v[118:119]
	v_pk_fma_f32 v[192:193], v[88:89], v[124:125], v[120:121]
	v_pk_fma_f32 v[194:195], v[82:83], v[106:107], v[102:103]
	v_pk_fma_f32 v[196:197], v[84:85], v[108:109], v[104:105]
	v_pk_fma_f32 v[190:191], v[94:95], v[126:127], v[190:191]
	v_pk_fma_f32 v[192:193], v[96:97], v[128:129], v[192:193]
	v_pk_fma_f32 v[194:195], v[90:91], v[110:111], v[194:195]
	v_pk_fma_f32 v[196:197], v[92:93], v[112:113], v[196:197]
	v_pk_fma_f32 v[190:191], v[78:79], v[114:115], v[190:191]
	v_pk_fma_f32 v[192:193], v[80:81], v[116:117], v[192:193]
	v_pk_fma_f32 v[194:195], v[74:75], v[98:99], v[194:195]
	v_pk_fma_f32 v[196:197], v[76:77], v[100:101], v[196:197]
	v_pk_mul_f32 v[198:199], v[190:191], s[50:51]
	v_pk_mul_f32 v[200:201], v[192:193], s[50:51]
	v_exp_f32_e32 v198, v198
	v_exp_f32_e32 v199, v199
	v_exp_f32_e32 v200, v200
	v_exp_f32_e32 v201, v201
	v_pk_add_f32 v[198:199], v[198:199], v[236:237]
	v_pk_add_f32 v[200:201], v[200:201], v[236:237]
	v_rcp_f32_e32 v198, v198
	v_rcp_f32_e32 v199, v199
	v_rcp_f32_e32 v200, v200
	v_rcp_f32_e32 v201, v201
	v_pk_mul_f32 v[190:191], v[190:191], v[198:199]
	v_pk_mul_f32 v[192:193], v[192:193], v[200:201]
	v_pk_mul_f32 v[190:191], v[190:191], v[194:195]
	v_pk_mul_f32 v[192:193], v[192:193], v[196:197]
	v_cvt_pk_bf16_f32 v234, v190, v191
	v_cvt_pk_bf16_f32 v235, v192, v193
	v_cmp_gt_i32_e32 vcc, s3, v230
	s_and_b64 vcc, vcc, s[52:53]
	s_nop 0
	v_permlane16_swap_b32_e32 v232, v234
	v_permlane16_swap_b32_e32 v233, v235
	s_and_saveexec_b64 s[0:1], vcc
	global_store_dwordx4 v231, v[232:235], s[12:13]
	s_mov_b64 exec, s[0:1]
	v_pk_fma_f32 v[190:191], v[78:79], v[122:123], v[118:119]
	v_pk_fma_f32 v[192:193], v[80:81], v[124:125], v[120:121]
	v_pk_fma_f32 v[194:195], v[74:75], v[106:107], v[102:103]
	v_pk_fma_f32 v[196:197], v[76:77], v[108:109], v[104:105]
	v_add_u32_e32 v230, 0x7e, v186
	v_add_u32_e32 v231, 0xad400, v187
	v_pk_fma_f32 v[190:191], v[86:87], v[126:127], v[190:191]
	v_pk_fma_f32 v[192:193], v[88:89], v[128:129], v[192:193]
	v_pk_fma_f32 v[194:195], v[82:83], v[110:111], v[194:195]
	v_pk_fma_f32 v[196:197], v[84:85], v[112:113], v[196:197]
	v_pk_fma_f32 v[190:191], v[70:71], v[114:115], v[190:191]
	v_pk_fma_f32 v[192:193], v[72:73], v[116:117], v[192:193]
	v_pk_fma_f32 v[194:195], v[66:67], v[98:99], v[194:195]
	v_pk_fma_f32 v[196:197], v[68:69], v[100:101], v[196:197]
	v_pk_mul_f32 v[198:199], v[190:191], s[50:51]
	v_pk_mul_f32 v[200:201], v[192:193], s[50:51]
	v_exp_f32_e32 v198, v198
	v_exp_f32_e32 v199, v199
	v_exp_f32_e32 v200, v200
	v_exp_f32_e32 v201, v201
	v_pk_add_f32 v[198:199], v[198:199], v[236:237]
	v_pk_add_f32 v[200:201], v[200:201], v[236:237]
	v_rcp_f32_e32 v198, v198
	v_rcp_f32_e32 v199, v199
	v_rcp_f32_e32 v200, v200
	v_rcp_f32_e32 v201, v201
	v_pk_mul_f32 v[190:191], v[190:191], v[198:199]
	v_pk_mul_f32 v[192:193], v[192:193], v[200:201]
	v_pk_mul_f32 v[190:191], v[190:191], v[194:195]
	v_pk_mul_f32 v[192:193], v[192:193], v[196:197]
	v_cvt_pk_bf16_f32 v232, v190, v191
	v_cvt_pk_bf16_f32 v233, v192, v193
	v_pk_fma_f32 v[190:191], v[70:71], v[122:123], v[118:119]
	v_pk_fma_f32 v[192:193], v[72:73], v[124:125], v[120:121]
	v_pk_fma_f32 v[194:195], v[66:67], v[106:107], v[102:103]
	v_pk_fma_f32 v[196:197], v[68:69], v[108:109], v[104:105]
	v_pk_fma_f32 v[190:191], v[78:79], v[126:127], v[190:191]
	v_pk_fma_f32 v[192:193], v[80:81], v[128:129], v[192:193]
	v_pk_fma_f32 v[194:195], v[74:75], v[110:111], v[194:195]
	v_pk_fma_f32 v[196:197], v[76:77], v[112:113], v[196:197]
	v_fmac_f32_dpp v190, v94, v114 row_ror:15 row_mask:0xf bank_mask:0xf
	v_fmac_f32_dpp v191, v95, v115 row_ror:15 row_mask:0xf bank_mask:0xf
	v_fmac_f32_dpp v192, v96, v116 row_ror:15 row_mask:0xf bank_mask:0xf
	v_fmac_f32_dpp v193, v97, v117 row_ror:15 row_mask:0xf bank_mask:0xf
	v_fmac_f32_dpp v194, v90, v98 row_ror:15 row_mask:0xf bank_mask:0xf
	v_fmac_f32_dpp v195, v91, v99 row_ror:15 row_mask:0xf bank_mask:0xf
	v_fmac_f32_dpp v196, v92, v100 row_ror:15 row_mask:0xf bank_mask:0xf
	v_fmac_f32_dpp v197, v93, v101 row_ror:15 row_mask:0xf bank_mask:0xf
	v_pk_mul_f32 v[198:199], v[190:191], s[50:51]
	v_pk_mul_f32 v[200:201], v[192:193], s[50:51]
	v_exp_f32_e32 v198, v198
	v_exp_f32_e32 v199, v199
	v_exp_f32_e32 v200, v200
	v_exp_f32_e32 v201, v201
	v_pk_add_f32 v[198:199], v[198:199], v[236:237]
	v_pk_add_f32 v[200:201], v[200:201], v[236:237]
	v_rcp_f32_e32 v198, v198
	v_rcp_f32_e32 v199, v199
	v_rcp_f32_e32 v200, v200
	v_rcp_f32_e32 v201, v201
	v_pk_mul_f32 v[190:191], v[190:191], v[198:199]
	v_pk_mul_f32 v[192:193], v[192:193], v[200:201]
	v_pk_mul_f32 v[190:191], v[190:191], v[194:195]
	v_pk_mul_f32 v[192:193], v[192:193], v[196:197]
	v_cvt_pk_bf16_f32 v234, v190, v191
	v_cvt_pk_bf16_f32 v235, v192, v193
	v_cmp_gt_i32_e32 vcc, s3, v230
	s_and_b64 vcc, vcc, s[54:55]
	s_nop 0
	v_permlane16_swap_b32_e32 v232, v234
	v_permlane16_swap_b32_e32 v233, v235
	s_and_saveexec_b64 s[0:1], vcc
	global_store_dwordx4 v231, v[232:235], s[12:13]
	s_mov_b64 exec, s[0:1]
	s_waitcnt lgkmcnt(0)
	v_pk_fma_f32 v[190:191], v[62:63], v[134:135], v[142:143]
	v_pk_fma_f32 v[192:193], v[64:65], v[136:137], v[144:145]
	v_pk_fma_f32 v[194:195], v[58:59], v[150:151], v[158:159]
	v_pk_fma_f32 v[196:197], v[60:61], v[152:153], v[160:161]
	v_add_u32_e32 v230, 0, v186
	v_fmac_f32_dpp v190, v38, v130 row_ror:1 row_mask:0xf bank_mask:0xf
	v_fmac_f32_dpp v191, v39, v131 row_ror:1 row_mask:0xf bank_mask:0xf
	v_fmac_f32_dpp v192, v40, v132 row_ror:1 row_mask:0xf bank_mask:0xf
	v_fmac_f32_dpp v193, v41, v133 row_ror:1 row_mask:0xf bank_mask:0xf
	v_fmac_f32_dpp v194, v34, v146 row_ror:1 row_mask:0xf bank_mask:0xf
	v_fmac_f32_dpp v195, v35, v147 row_ror:1 row_mask:0xf bank_mask:0xf
	v_fmac_f32_dpp v196, v36, v148 row_ror:1 row_mask:0xf bank_mask:0xf
	v_fmac_f32_dpp v197, v37, v149 row_ror:1 row_mask:0xf bank_mask:0xf
	v_pk_fma_f32 v[190:191], v[54:55], v[138:139], v[190:191]
	v_pk_fma_f32 v[192:193], v[56:57], v[140:141], v[192:193]
	v_pk_fma_f32 v[194:195], v[50:51], v[154:155], v[194:195]
	v_pk_fma_f32 v[196:197], v[52:53], v[156:157], v[196:197]
	v_pk_mul_f32 v[198:199], v[190:191], s[50:51]
	v_pk_mul_f32 v[200:201], v[192:193], s[50:51]
	v_exp_f32_e32 v198, v198
	v_exp_f32_e32 v199, v199
	v_exp_f32_e32 v200, v200
	v_exp_f32_e32 v201, v201
	v_pk_add_f32 v[198:199], v[198:199], v[236:237]
	v_pk_add_f32 v[200:201], v[200:201], v[236:237]
	v_rcp_f32_e32 v198, v198
	v_rcp_f32_e32 v199, v199
	v_rcp_f32_e32 v200, v200
	v_rcp_f32_e32 v201, v201
	v_pk_mul_f32 v[190:191], v[190:191], v[198:199]
	v_pk_mul_f32 v[192:193], v[192:193], v[200:201]
	v_pk_mul_f32 v[190:191], v[190:191], v[194:195]
	v_pk_mul_f32 v[192:193], v[192:193], v[196:197]
	v_cvt_pk_bf16_f32 v232, v190, v191
	v_cvt_pk_bf16_f32 v233, v192, v193
	v_pk_fma_f32 v[190:191], v[54:55], v[134:135], v[142:143]
	v_pk_fma_f32 v[192:193], v[56:57], v[136:137], v[144:145]
	v_pk_fma_f32 v[194:195], v[50:51], v[150:151], v[158:159]
	v_pk_fma_f32 v[196:197], v[52:53], v[152:153], v[160:161]
	v_pk_fma_f32 v[190:191], v[62:63], v[130:131], v[190:191]
	v_pk_fma_f32 v[192:193], v[64:65], v[132:133], v[192:193]
	v_pk_fma_f32 v[194:195], v[58:59], v[146:147], v[194:195]
	v_pk_fma_f32 v[196:197], v[60:61], v[148:149], v[196:197]
	v_pk_fma_f32 v[190:191], v[46:47], v[138:139], v[190:191]
	v_pk_fma_f32 v[192:193], v[48:49], v[140:141], v[192:193]
	v_pk_fma_f32 v[194:195], v[42:43], v[154:155], v[194:195]
	v_pk_fma_f32 v[196:197], v[44:45], v[156:157], v[196:197]
	v_pk_mul_f32 v[198:199], v[190:191], s[50:51]
	v_pk_mul_f32 v[200:201], v[192:193], s[50:51]
	v_exp_f32_e32 v198, v198
	v_exp_f32_e32 v199, v199
	v_exp_f32_e32 v200, v200
	v_exp_f32_e32 v201, v201
	v_pk_add_f32 v[198:199], v[198:199], v[236:237]
	v_pk_add_f32 v[200:201], v[200:201], v[236:237]
	v_rcp_f32_e32 v198, v198
	v_rcp_f32_e32 v199, v199
	v_rcp_f32_e32 v200, v200
	v_rcp_f32_e32 v201, v201
	v_pk_mul_f32 v[190:191], v[190:191], v[198:199]
	v_pk_mul_f32 v[192:193], v[192:193], v[200:201]
	v_pk_mul_f32 v[190:191], v[190:191], v[194:195]
	v_pk_mul_f32 v[192:193], v[192:193], v[196:197]
	v_cvt_pk_bf16_f32 v234, v190, v191
	v_cvt_pk_bf16_f32 v235, v192, v193
	v_cmp_gt_i32_e32 vcc, s3, v230
	s_and_b64 vcc, vcc, s[52:53]
	s_nop 0
	v_permlane16_swap_b32_e32 v232, v234
	v_permlane16_swap_b32_e32 v233, v235
	s_and_saveexec_b64 s[0:1], vcc
	global_store_dwordx4 v187, v[232:235], s[12:13] offset:128
	s_mov_b64 exec, s[0:1]
	v_pk_fma_f32 v[190:191], v[46:47], v[134:135], v[142:143]
	v_pk_fma_f32 v[192:193], v[48:49], v[136:137], v[144:145]
	v_pk_fma_f32 v[194:195], v[42:43], v[150:151], v[158:159]
	v_pk_fma_f32 v[196:197], v[44:45], v[152:153], v[160:161]
	v_add_u32_e32 v230, 2, v186
	v_add_u32_e32 v231, 0x2c00, v187
	v_pk_fma_f32 v[190:191], v[54:55], v[130:131], v[190:191]
	v_pk_fma_f32 v[192:193], v[56:57], v[132:133], v[192:193]
	v_pk_fma_f32 v[194:195], v[50:51], v[146:147], v[194:195]
	v_pk_fma_f32 v[196:197], v[52:53], v[148:149], v[196:197]
	v_pk_fma_f32 v[190:191], v[38:39], v[138:139], v[190:191]
	v_pk_fma_f32 v[192:193], v[40:41], v[140:141], v[192:193]
	v_pk_fma_f32 v[194:195], v[34:35], v[154:155], v[194:195]
	v_pk_fma_f32 v[196:197], v[36:37], v[156:157], v[196:197]
	v_pk_mul_f32 v[198:199], v[190:191], s[50:51]
	v_pk_mul_f32 v[200:201], v[192:193], s[50:51]
	v_exp_f32_e32 v198, v198
	v_exp_f32_e32 v199, v199
	v_exp_f32_e32 v200, v200
	v_exp_f32_e32 v201, v201
	v_pk_add_f32 v[198:199], v[198:199], v[236:237]
	v_pk_add_f32 v[200:201], v[200:201], v[236:237]
	v_rcp_f32_e32 v198, v198
	v_rcp_f32_e32 v199, v199
	v_rcp_f32_e32 v200, v200
	v_rcp_f32_e32 v201, v201
	v_pk_mul_f32 v[190:191], v[190:191], v[198:199]
	v_pk_mul_f32 v[192:193], v[192:193], v[200:201]
	v_pk_mul_f32 v[190:191], v[190:191], v[194:195]
	v_pk_mul_f32 v[192:193], v[192:193], v[196:197]
	v_cvt_pk_bf16_f32 v232, v190, v191
	v_cvt_pk_bf16_f32 v233, v192, v193
	v_pk_fma_f32 v[190:191], v[38:39], v[134:135], v[142:143]
	v_pk_fma_f32 v[192:193], v[40:41], v[136:137], v[144:145]
	v_pk_fma_f32 v[194:195], v[34:35], v[150:151], v[158:159]
	v_pk_fma_f32 v[196:197], v[36:37], v[152:153], v[160:161]
	v_pk_fma_f32 v[190:191], v[46:47], v[130:131], v[190:191]
	v_pk_fma_f32 v[192:193], v[48:49], v[132:133], v[192:193]
	v_pk_fma_f32 v[194:195], v[42:43], v[146:147], v[194:195]
	v_pk_fma_f32 v[196:197], v[44:45], v[148:149], v[196:197]
	v_fmac_f32_dpp v190, v62, v138 row_ror:15 row_mask:0xf bank_mask:0xf
	v_fmac_f32_dpp v191, v63, v139 row_ror:15 row_mask:0xf bank_mask:0xf
	v_fmac_f32_dpp v192, v64, v140 row_ror:15 row_mask:0xf bank_mask:0xf
	v_fmac_f32_dpp v193, v65, v141 row_ror:15 row_mask:0xf bank_mask:0xf
	v_fmac_f32_dpp v194, v58, v154 row_ror:15 row_mask:0xf bank_mask:0xf
	v_fmac_f32_dpp v195, v59, v155 row_ror:15 row_mask:0xf bank_mask:0xf
	v_fmac_f32_dpp v196, v60, v156 row_ror:15 row_mask:0xf bank_mask:0xf
	v_fmac_f32_dpp v197, v61, v157 row_ror:15 row_mask:0xf bank_mask:0xf
	v_pk_mul_f32 v[198:199], v[190:191], s[50:51]
	v_pk_mul_f32 v[200:201], v[192:193], s[50:51]
	v_exp_f32_e32 v198, v198
	v_exp_f32_e32 v199, v199
	v_exp_f32_e32 v200, v200
	v_exp_f32_e32 v201, v201
	v_pk_add_f32 v[198:199], v[198:199], v[236:237]
	v_pk_add_f32 v[200:201], v[200:201], v[236:237]
	v_rcp_f32_e32 v198, v198
	v_rcp_f32_e32 v199, v199
	v_rcp_f32_e32 v200, v200
	v_rcp_f32_e32 v201, v201
	v_pk_mul_f32 v[190:191], v[190:191], v[198:199]
	v_pk_mul_f32 v[192:193], v[192:193], v[200:201]
	v_pk_mul_f32 v[190:191], v[190:191], v[194:195]
	v_pk_mul_f32 v[192:193], v[192:193], v[196:197]
	v_cvt_pk_bf16_f32 v234, v190, v191
	v_cvt_pk_bf16_f32 v235, v192, v193
	v_cmp_gt_i32_e32 vcc, s3, v230
	s_and_b64 vcc, vcc, s[54:55]
	s_nop 0
	v_permlane16_swap_b32_e32 v232, v234
	v_permlane16_swap_b32_e32 v233, v235
	s_and_saveexec_b64 s[0:1], vcc
	global_store_dwordx4 v231, v[232:235], s[12:13] offset:128
	s_mov_b64 exec, s[0:1]
	v_pk_fma_f32 v[190:191], v[30:31], v[134:135], v[142:143]
	v_pk_fma_f32 v[192:193], v[32:33], v[136:137], v[144:145]
	v_pk_fma_f32 v[194:195], v[26:27], v[150:151], v[158:159]
	v_pk_fma_f32 v[196:197], v[28:29], v[152:153], v[160:161]
	v_add_u32_e32 v230, 0x7c, v186
	v_add_u32_e32 v231, 0xaa800, v187
	v_fmac_f32_dpp v190, v6, v130 row_ror:1 row_mask:0xf bank_mask:0xf
	v_fmac_f32_dpp v191, v7, v131 row_ror:1 row_mask:0xf bank_mask:0xf
	v_fmac_f32_dpp v192, v8, v132 row_ror:1 row_mask:0xf bank_mask:0xf
	v_fmac_f32_dpp v193, v9, v133 row_ror:1 row_mask:0xf bank_mask:0xf
	v_fmac_f32_dpp v194, v2, v146 row_ror:1 row_mask:0xf bank_mask:0xf
	v_fmac_f32_dpp v195, v3, v147 row_ror:1 row_mask:0xf bank_mask:0xf
	v_fmac_f32_dpp v196, v4, v148 row_ror:1 row_mask:0xf bank_mask:0xf
	v_fmac_f32_dpp v197, v5, v149 row_ror:1 row_mask:0xf bank_mask:0xf
	v_pk_fma_f32 v[190:191], v[22:23], v[138:139], v[190:191]
	v_pk_fma_f32 v[192:193], v[24:25], v[140:141], v[192:193]
	v_pk_fma_f32 v[194:195], v[18:19], v[154:155], v[194:195]
	v_pk_fma_f32 v[196:197], v[20:21], v[156:157], v[196:197]
	v_pk_mul_f32 v[198:199], v[190:191], s[50:51]
	v_pk_mul_f32 v[200:201], v[192:193], s[50:51]
	v_exp_f32_e32 v198, v198
	v_exp_f32_e32 v199, v199
	v_exp_f32_e32 v200, v200
	v_exp_f32_e32 v201, v201
	v_pk_add_f32 v[198:199], v[198:199], v[236:237]
	v_pk_add_f32 v[200:201], v[200:201], v[236:237]
	v_rcp_f32_e32 v198, v198
	v_rcp_f32_e32 v199, v199
	v_rcp_f32_e32 v200, v200
	v_rcp_f32_e32 v201, v201
	v_pk_mul_f32 v[190:191], v[190:191], v[198:199]
	v_pk_mul_f32 v[192:193], v[192:193], v[200:201]
	v_pk_mul_f32 v[190:191], v[190:191], v[194:195]
	v_pk_mul_f32 v[192:193], v[192:193], v[196:197]
	v_cvt_pk_bf16_f32 v232, v190, v191
	v_cvt_pk_bf16_f32 v233, v192, v193
	v_pk_fma_f32 v[190:191], v[22:23], v[134:135], v[142:143]
	v_pk_fma_f32 v[192:193], v[24:25], v[136:137], v[144:145]
	v_pk_fma_f32 v[194:195], v[18:19], v[150:151], v[158:159]
	v_pk_fma_f32 v[196:197], v[20:21], v[152:153], v[160:161]
	v_pk_fma_f32 v[190:191], v[30:31], v[130:131], v[190:191]
	v_pk_fma_f32 v[192:193], v[32:33], v[132:133], v[192:193]
	v_pk_fma_f32 v[194:195], v[26:27], v[146:147], v[194:195]
	v_pk_fma_f32 v[196:197], v[28:29], v[148:149], v[196:197]
	v_pk_fma_f32 v[190:191], v[14:15], v[138:139], v[190:191]
	v_pk_fma_f32 v[192:193], v[16:17], v[140:141], v[192:193]
	v_pk_fma_f32 v[194:195], v[10:11], v[154:155], v[194:195]
	v_pk_fma_f32 v[196:197], v[12:13], v[156:157], v[196:197]
	v_pk_mul_f32 v[198:199], v[190:191], s[50:51]
	v_pk_mul_f32 v[200:201], v[192:193], s[50:51]
	v_exp_f32_e32 v198, v198
	v_exp_f32_e32 v199, v199
	v_exp_f32_e32 v200, v200
	v_exp_f32_e32 v201, v201
	v_pk_add_f32 v[198:199], v[198:199], v[236:237]
	v_pk_add_f32 v[200:201], v[200:201], v[236:237]
	v_rcp_f32_e32 v198, v198
	v_rcp_f32_e32 v199, v199
	v_rcp_f32_e32 v200, v200
	v_rcp_f32_e32 v201, v201
	v_pk_mul_f32 v[190:191], v[190:191], v[198:199]
	v_pk_mul_f32 v[192:193], v[192:193], v[200:201]
	v_pk_mul_f32 v[190:191], v[190:191], v[194:195]
	v_pk_mul_f32 v[192:193], v[192:193], v[196:197]
	v_cvt_pk_bf16_f32 v234, v190, v191
	v_cvt_pk_bf16_f32 v235, v192, v193
	v_cmp_gt_i32_e32 vcc, s3, v230
	s_and_b64 vcc, vcc, s[52:53]
	s_nop 0
	v_permlane16_swap_b32_e32 v232, v234
	v_permlane16_swap_b32_e32 v233, v235
	s_and_saveexec_b64 s[0:1], vcc
	global_store_dwordx4 v231, v[232:235], s[12:13] offset:128
	s_mov_b64 exec, s[0:1]
	v_pk_fma_f32 v[190:191], v[14:15], v[134:135], v[142:143]
	v_pk_fma_f32 v[192:193], v[16:17], v[136:137], v[144:145]
	v_pk_fma_f32 v[194:195], v[10:11], v[150:151], v[158:159]
	v_pk_fma_f32 v[196:197], v[12:13], v[152:153], v[160:161]
	v_add_u32_e32 v230, 0x7e, v186
	v_add_u32_e32 v231, 0xad400, v187
	v_pk_fma_f32 v[190:191], v[22:23], v[130:131], v[190:191]
	v_pk_fma_f32 v[192:193], v[24:25], v[132:133], v[192:193]
	v_pk_fma_f32 v[194:195], v[18:19], v[146:147], v[194:195]
	v_pk_fma_f32 v[196:197], v[20:21], v[148:149], v[196:197]
	v_pk_fma_f32 v[190:191], v[6:7], v[138:139], v[190:191]
	v_pk_fma_f32 v[192:193], v[8:9], v[140:141], v[192:193]
	v_pk_fma_f32 v[194:195], v[2:3], v[154:155], v[194:195]
	v_pk_fma_f32 v[196:197], v[4:5], v[156:157], v[196:197]
	v_pk_mul_f32 v[198:199], v[190:191], s[50:51]
	v_pk_mul_f32 v[200:201], v[192:193], s[50:51]
	v_exp_f32_e32 v198, v198
	v_exp_f32_e32 v199, v199
	v_exp_f32_e32 v200, v200
	v_exp_f32_e32 v201, v201
	v_pk_add_f32 v[198:199], v[198:199], v[236:237]
	v_pk_add_f32 v[200:201], v[200:201], v[236:237]
	v_rcp_f32_e32 v198, v198
	v_rcp_f32_e32 v199, v199
	v_rcp_f32_e32 v200, v200
	v_rcp_f32_e32 v201, v201
	v_pk_mul_f32 v[190:191], v[190:191], v[198:199]
	v_pk_mul_f32 v[192:193], v[192:193], v[200:201]
	v_pk_mul_f32 v[190:191], v[190:191], v[194:195]
	v_pk_mul_f32 v[192:193], v[192:193], v[196:197]
	v_cvt_pk_bf16_f32 v232, v190, v191
	v_cvt_pk_bf16_f32 v233, v192, v193
	v_pk_fma_f32 v[190:191], v[6:7], v[134:135], v[142:143]
	v_pk_fma_f32 v[192:193], v[8:9], v[136:137], v[144:145]
	v_pk_fma_f32 v[194:195], v[2:3], v[150:151], v[158:159]
	v_pk_fma_f32 v[196:197], v[4:5], v[152:153], v[160:161]
	v_pk_fma_f32 v[190:191], v[14:15], v[130:131], v[190:191]
	v_pk_fma_f32 v[192:193], v[16:17], v[132:133], v[192:193]
	v_pk_fma_f32 v[194:195], v[10:11], v[146:147], v[194:195]
	v_pk_fma_f32 v[196:197], v[12:13], v[148:149], v[196:197]
	v_fmac_f32_dpp v190, v30, v138 row_ror:15 row_mask:0xf bank_mask:0xf
	v_fmac_f32_dpp v191, v31, v139 row_ror:15 row_mask:0xf bank_mask:0xf
	v_fmac_f32_dpp v192, v32, v140 row_ror:15 row_mask:0xf bank_mask:0xf
	v_fmac_f32_dpp v193, v33, v141 row_ror:15 row_mask:0xf bank_mask:0xf
	v_fmac_f32_dpp v194, v26, v154 row_ror:15 row_mask:0xf bank_mask:0xf
	v_fmac_f32_dpp v195, v27, v155 row_ror:15 row_mask:0xf bank_mask:0xf
	v_fmac_f32_dpp v196, v28, v156 row_ror:15 row_mask:0xf bank_mask:0xf
	v_fmac_f32_dpp v197, v29, v157 row_ror:15 row_mask:0xf bank_mask:0xf
	v_pk_mul_f32 v[198:199], v[190:191], s[50:51]
	v_pk_mul_f32 v[200:201], v[192:193], s[50:51]
	v_exp_f32_e32 v198, v198
	v_exp_f32_e32 v199, v199
	v_exp_f32_e32 v200, v200
	v_exp_f32_e32 v201, v201
	v_pk_add_f32 v[198:199], v[198:199], v[236:237]
	v_pk_add_f32 v[200:201], v[200:201], v[236:237]
	v_rcp_f32_e32 v198, v198
	v_rcp_f32_e32 v199, v199
	v_rcp_f32_e32 v200, v200
	v_rcp_f32_e32 v201, v201
	v_pk_mul_f32 v[190:191], v[190:191], v[198:199]
	v_pk_mul_f32 v[192:193], v[192:193], v[200:201]
	v_pk_mul_f32 v[190:191], v[190:191], v[194:195]
	v_pk_mul_f32 v[192:193], v[192:193], v[196:197]
	v_cvt_pk_bf16_f32 v234, v190, v191
	v_cvt_pk_bf16_f32 v235, v192, v193
	v_cmp_gt_i32_e32 vcc, s3, v230
	s_and_b64 vcc, vcc, s[54:55]
	s_nop 0
	v_permlane16_swap_b32_e32 v232, v234
	v_permlane16_swap_b32_e32 v233, v235
	s_and_saveexec_b64 s[0:1], vcc
	global_store_dwordx4 v231, v[232:235], s[12:13] offset:128
	s_mov_b64 exec, s[0:1]
